# final_rows: the 64-lane sum-of-squares reduction uses DPP + permlane16/32 swaps instead of six ds_bpermute round trips (bit-identical)
# speedup vs baseline: 1.0032x; 1.0032x over previous
; __device__ __forceinline__ float lane_xor(float v, int lane, int o) { return __builtin_bit_cast(float, __builtin_amdgcn_ds_bpermute((lane ^ o) << 2, __builtin_bit_cast(int, v))); }
; __device__ __forceinline__ float wave_sum(float v, int lane) {
; #pragma unroll
;     for (int o = 1; o < 64; o <<= 1) v += lane_xor(v, lane, o);
;     return v;
; __device__ __forceinline__ void final_rows(float* OUT, const float* gain, int gw, int ngw) {
;     ...
;     for (int r = gw; r < NSEQ * SEQ; r += ngw) {
;         f32x4* hp = (f32x4*)(OUT + (size_t)r * DM) + lane;
;         f32x4 v[4]; float s = 0.f;
; #pragma unroll
;         for (int j = 0; j < 4; ++j) { v[j] = hp[64 * j]; s += (v[j].x * v[j].x + v[j].y * v[j].y) + (v[j].z * v[j].z + v[j].w * v[j].w); }
;         const float rstd = 1.0f / sqrtf(wave_sum(s, lane) * (1.0f / DM) + EPSN);
; #pragma unroll
;         for (int j = 0; j < 4; ++j) { const f32x4 y_ = v[j] * rstd * g[j]; __builtin_nontemporal_store(y_, &hp[64 * j]); }
;     }
.LBB0_1193:
	global_load_dwordx4 v[26:29], v[18:19], off offset:-3072
	s_add_i32 s4, s4, s6
	s_cmp_gt_i32 s4, 0x13fff
	s_waitcnt vmcnt(0)
	v_pk_mul_f32 v[30:31], v[28:29], v[28:29]
	v_pk_mul_f32 v[32:33], v[26:27], v[26:27]
	s_nop 0
	v_pk_mov_b32 v[34:35], v[32:33], v[30:31] op_sel:[1,0]
	v_mov_b32_e32 v33, v31
	v_pk_add_f32 v[42:43], v[34:35], v[32:33]
	global_load_dwordx4 v[30:33], v[18:19], off offset:-2048
	v_pk_add_f32 v[42:43], v[42:43], v[42:43] op_sel:[0,1] op_sel_hi:[1,0]
	s_waitcnt vmcnt(0)
	v_pk_mul_f32 v[34:35], v[32:33], v[32:33]
	v_pk_mul_f32 v[36:37], v[30:31], v[30:31]
	s_nop 0
	v_pk_mov_b32 v[38:39], v[36:37], v[34:35] op_sel:[1,0]
	v_mov_b32_e32 v37, v35
	v_pk_add_f32 v[44:45], v[38:39], v[36:37]
	global_load_dwordx4 v[34:37], v[18:19], off offset:-1024
	global_load_dwordx4 v[38:41], v[18:19], off
	v_pk_add_f32 v[44:45], v[44:45], v[44:45] op_sel:[0,1] op_sel_hi:[1,0]
	s_waitcnt vmcnt(0)
	v_mul_f32_e32 v0, v38, v38
	v_mul_f32_e32 v46, v39, v39
	v_mov_b32_e32 v43, v0
	v_mov_b32_e32 v45, v46
	v_mul_f32_e32 v0, v35, v35
	v_mul_f32_e32 v47, v40, v40
	v_pk_add_f32 v[42:43], v[42:43], v[44:45]
	v_pk_fma_f32 v[44:45], v[34:35], v[34:35], v[0:1] op_sel_hi:[1,1,0]
	v_mul_f32_e32 v0, v37, v37
	v_mul_f32_e32 v48, v41, v41
	v_mov_b32_e32 v45, v47
	v_pk_fma_f32 v[46:47], v[36:37], v[36:37], v[0:1] op_sel_hi:[1,1,0]
	s_nop 0
	v_mov_b32_e32 v47, v48
	v_pk_add_f32 v[44:45], v[44:45], v[46:47]
	s_nop 0
	v_pk_add_f32 v[42:43], v[42:43], v[44:45]
	s_nop 0
	v_add_f32_e32 v0, v42, v43
	s_nop 1
	v_add_f32_dpp v0, v0, v0 quad_perm:[1,0,3,2] row_mask:0xf bank_mask:0xf
	s_nop 1
	v_add_f32_dpp v0, v0, v0 quad_perm:[2,3,0,1] row_mask:0xf bank_mask:0xf
	s_nop 1
	v_add_f32_dpp v0, v0, v0 row_half_mirror row_mask:0xf bank_mask:0xf
	s_nop 1
	v_add_f32_dpp v0, v0, v0 row_mirror row_mask:0xf bank_mask:0xf
	v_mov_b32_e32 v42, v0
	s_nop 1
	v_permlane16_swap_b32_e32 v0, v42
	v_add_f32_e32 v0, v0, v42
	v_mov_b32_e32 v42, v0
	s_nop 1
	v_permlane32_swap_b32_e32 v0, v42
	v_add_f32_e32 v0, v0, v42
	v_fmamk_f32 v0, v0, 0x3a800000, v218
	v_cmp_gt_f32_e32 vcc, s11, v0
	v_mul_f32_e32 v42, 0x4f800000, v0
	s_nop 0
	v_cndmask_b32_e32 v0, v0, v42, vcc
	v_sqrt_f32_e32 v42, v0
	s_nop 0
	v_add_u32_e32 v43, -1, v42
	v_fma_f32 v44, -v43, v42, v0
	v_cmp_ge_f32_e64 s[0:1], 0, v44
	v_add_u32_e32 v44, 1, v42
	s_nop 0
	v_cndmask_b32_e64 v43, v42, v43, s[0:1]
	v_fma_f32 v42, -v44, v42, v0
	v_cmp_lt_f32_e64 s[0:1], 0, v42
	s_nop 1
	v_cndmask_b32_e64 v42, v43, v44, s[0:1]
	v_mul_f32_e32 v43, 0x37800000, v42
	v_cndmask_b32_e32 v42, v42, v43, vcc
	v_cmp_class_f32_e32 vcc, v0, v49
	s_nop 1
	v_cndmask_b32_e32 v0, v42, v0, vcc
	v_div_scale_f32 v42, s[0:1], v0, v0, 1.0
	v_rcp_f32_e32 v43, v42
	s_nop 0
	v_fma_f32 v44, -v42, v43, 1.0
	v_fmac_f32_e32 v43, v44, v43
	v_div_scale_f32 v44, vcc, 1.0, v0, 1.0
	v_mul_f32_e32 v45, v44, v43
	v_fma_f32 v46, -v42, v45, v44
	v_fmac_f32_e32 v45, v46, v43
	v_fma_f32 v42, -v42, v45, v44
	v_div_fmas_f32 v42, v42, v43, v45
	v_div_fixup_f32 v0, v42, v0, 1.0
	v_pk_mul_f32 v[26:27], v[26:27], v[0:1] op_sel_hi:[1,0]
	v_pk_mul_f32 v[28:29], v[28:29], v[0:1] op_sel_hi:[1,0]
	v_pk_mul_f32 v[26:27], v[2:3], v[26:27]
	v_pk_mul_f32 v[28:29], v[4:5], v[28:29]
	global_store_dwordx4 v[18:19], v[26:29], off offset:-3072 nt
	s_nop 1
	v_pk_mul_f32 v[26:27], v[30:31], v[0:1] op_sel_hi:[1,0]
	v_pk_mul_f32 v[28:29], v[32:33], v[0:1] op_sel_hi:[1,0]
	v_pk_mul_f32 v[26:27], v[6:7], v[26:27]
	v_pk_mul_f32 v[28:29], v[8:9], v[28:29]
	global_store_dwordx4 v[18:19], v[26:29], off offset:-2048 nt
	s_nop 1
	v_pk_mul_f32 v[26:27], v[34:35], v[0:1] op_sel_hi:[1,0]
	v_pk_mul_f32 v[28:29], v[36:37], v[0:1] op_sel_hi:[1,0]
	v_pk_mul_f32 v[26:27], v[10:11], v[26:27]
	v_pk_mul_f32 v[28:29], v[12:13], v[28:29]
	global_store_dwordx4 v[18:19], v[26:29], off offset:-1024 nt
	s_nop 1
	v_pk_mul_f32 v[26:27], v[38:39], v[0:1] op_sel_hi:[1,0]
	v_pk_mul_f32 v[28:29], v[40:41], v[0:1] op_sel_hi:[1,0]
	v_pk_mul_f32 v[26:27], v[14:15], v[26:27]
	v_pk_mul_f32 v[28:29], v[16:17], v[28:29]
	global_store_dwordx4 v[18:19], v[26:29], off nt
	v_lshl_add_u64 v[18:19], v[18:19], 0, s[8:9]
	s_cbranch_scc0 .LBB0_1193
